# attention: 4-deep K-fragment read pipeline in QK^T (uses v240-v255), on top of lean GEMM K-loops
# speedup vs baseline: 1.0008x; 1.0002x over previous
.LBB0_346:
	s_add_i32 s12, s76, 0xffffc000
	s_and_b32 s12, s12, 0x4000
	s_add_i32 s68, s12, 0
	v_add_u32_e32 v2, s68, v222
	v_add_u32_e32 v16, s68, v223
	v_add_u32_e32 v17, s68, v224
	v_add_u32_e32 v234, s68, v225
	ds_read_b128 v[4:7], v2
	ds_read_b128 v[8:11], v2 offset:0x2000
	ds_read_b128 v[12:15], v16
	ds_read_b128 v[230:233], v16 offset:0x2000
	ds_read_b128 v[240:243], v17
	ds_read_b128 v[244:247], v17 offset:0x2000
	ds_read_b128 v[248:251], v234
	ds_read_b128 v[252:255], v234 offset:0x2000
	s_waitcnt lgkmcnt(6)
	v_mfma_f32_32x32x16_bf16 v[162:177], v[4:7], v[178:181], 0
	v_mfma_f32_32x32x16_bf16 v[146:161], v[8:11], v[178:181], 0
	ds_read_b128 v[4:7], v2 offset:0x80
	ds_read_b128 v[8:11], v2 offset:0x2080
	s_waitcnt lgkmcnt(6)
	v_mfma_f32_32x32x16_bf16 v[162:177], v[12:15], v[182:185], v[162:177]
	v_mfma_f32_32x32x16_bf16 v[146:161], v[230:233], v[182:185], v[146:161]
	ds_read_b128 v[12:15], v16 offset:0x80
	ds_read_b128 v[230:233], v16 offset:0x2080
	s_waitcnt lgkmcnt(6)
	v_mfma_f32_32x32x16_bf16 v[162:177], v[240:243], v[186:189], v[162:177]
	v_mfma_f32_32x32x16_bf16 v[146:161], v[244:247], v[186:189], v[146:161]
	ds_read_b128 v[240:243], v17 offset:0x80
	ds_read_b128 v[244:247], v17 offset:0x2080
	s_waitcnt lgkmcnt(6)
	v_mfma_f32_32x32x16_bf16 v[162:177], v[248:251], v[190:193], v[162:177]
	v_mfma_f32_32x32x16_bf16 v[146:161], v[252:255], v[190:193], v[146:161]
	ds_read_b128 v[248:251], v234 offset:0x80
	ds_read_b128 v[252:255], v234 offset:0x2080
	s_waitcnt lgkmcnt(6)
	v_mfma_f32_32x32x16_bf16 v[162:177], v[4:7], v[194:197], v[162:177]
	v_mfma_f32_32x32x16_bf16 v[146:161], v[8:11], v[194:197], v[146:161]
	s_waitcnt lgkmcnt(4)
	v_mfma_f32_32x32x16_bf16 v[162:177], v[12:15], v[198:201], v[162:177]
	v_mfma_f32_32x32x16_bf16 v[146:161], v[230:233], v[198:201], v[146:161]
	s_waitcnt lgkmcnt(2)
	v_mfma_f32_32x32x16_bf16 v[162:177], v[240:243], v[202:205], v[162:177]
	v_mfma_f32_32x32x16_bf16 v[146:161], v[244:247], v[202:205], v[146:161]
	s_waitcnt lgkmcnt(0)
	v_mfma_f32_32x32x16_bf16 v[162:177], v[248:251], v[206:209], v[162:177]
	s_cmp_ge_i32 s78, s63
	s_cselect_b64 s[12:13], -1, 0
	s_or_b64 s[12:13], s[66:67], s[12:13]
	s_and_b64 vcc, exec, s[12:13]
	v_mfma_f32_32x32x16_bf16 v[146:161], v[252:255], v[206:209], v[146:161]
	s_cbranch_vccnz .LBB0_349
	s_waitcnt vmcnt(0)
	s_add_i32 s12, s80, 2
	s_cmp_ge_i32 s12, s63
	s_waitcnt vmcnt(0) lgkmcnt(0)
	s_barrier
	s_cbranch_scc1 .LBB0_349
	s_add_i32 s12, s6, 64
	s_mov_b32 s13, s7
	s_lshl_b64 s[12:13], s[12:13], 12
	s_add_u32 s14, s48, s12
	s_addc_u32 s15, s49, s13
	s_add_u32 s12, s50, s12
	s_addc_u32 s13, s51, s13
	s_lshl_b32 s16, s77, 15
	s_add_i32 s16, s16, 0x10000
	s_cmp_lg_u32 s77, 2
	s_cselect_b32 s16, s16, 0x8000
	s_add_i32 s17, s68, s73
	v_lshl_add_u64 v[4:5], v[210:211], 1, s[14:15]
	s_mov_b32 m0, s17
	s_add_i32 s16, s62, s16
	global_load_lds_dwordx4 v[4:5], off
	v_lshl_add_u64 v[4:5], v[212:213], 1, s[12:13]
	s_mov_b32 m0, s16
	s_nop 0
	global_load_lds_dwordx4 v[4:5], off
	v_lshl_add_u64 v[4:5], v[4:5], 0, s[8:9]
	s_add_i32 m0, s16, 0x4000
	s_nop 0
	global_load_lds_dwordx4 v[4:5], off
	v_lshl_add_u64 v[4:5], v[214:215], 1, s[14:15]
	s_add_i32 m0, s17, 0x2000
	s_nop 0
	global_load_lds_dwordx4 v[4:5], off
	v_lshl_add_u64 v[4:5], v[218:219], 1, s[12:13]
	s_add_i32 m0, s16, 0x2000
	s_nop 0
	global_load_lds_dwordx4 v[4:5], off
	v_lshl_add_u64 v[4:5], v[4:5], 0, s[8:9]
	s_add_i32 m0, s16, 0x6000
	s_nop 0
	global_load_lds_dwordx4 v[4:5], off

	.amdhsa_kernel _Z10fwd_kernel4Args
		.amdhsa_group_segment_fixed_size 0
		.amdhsa_private_segment_fixed_size 0
		.amdhsa_kernarg_size 432
		.amdhsa_user_sgpr_count 2
		.amdhsa_user_sgpr_dispatch_ptr 0
		.amdhsa_user_sgpr_queue_ptr 0
		.amdhsa_user_sgpr_kernarg_segment_ptr 1
		.amdhsa_user_sgpr_dispatch_id 0
		.amdhsa_user_sgpr_kernarg_preload_length 0
		.amdhsa_user_sgpr_kernarg_preload_offset 0
		.amdhsa_user_sgpr_private_segment_size 0
		.amdhsa_uses_dynamic_stack 0
		.amdhsa_enable_private_segment 0
		.amdhsa_system_sgpr_workgroup_id_x 1
		.amdhsa_system_sgpr_workgroup_id_y 0
		.amdhsa_system_sgpr_workgroup_id_z 0
		.amdhsa_system_sgpr_workgroup_info 0
		.amdhsa_system_vgpr_workitem_id 0
		.amdhsa_next_free_vgpr 256
		.amdhsa_next_free_sgpr 102
		.amdhsa_accum_offset 256
		.amdhsa_reserve_vcc 1
		.amdhsa_float_round_mode_32 0
		.amdhsa_float_round_mode_16_64 0
		.amdhsa_float_denorm_mode_32 3
		.amdhsa_float_denorm_mode_16_64 3
		.amdhsa_dx10_clamp 1
		.amdhsa_ieee_mode 1
		.amdhsa_fp16_overflow 0
		.amdhsa_tg_split 0
		.amdhsa_exception_fp_ieee_invalid_op 0
		.amdhsa_exception_fp_denorm_src 0
		.amdhsa_exception_fp_ieee_div_zero 0
		.amdhsa_exception_fp_ieee_overflow 0
		.amdhsa_exception_fp_ieee_underflow 0
		.amdhsa_exception_fp_ieee_inexact 0
		.amdhsa_exception_int_div_zero 0
	.end_amdhsa_kernel

amdhsa.kernels:
  - .agpr_count:     0
    .args:
      - .offset:         0
        .size:           176
        .value_kind:     by_value
      - .offset:         176
        .size:           4
        .value_kind:     hidden_block_count_x
      - .offset:         180
        .size:           4
        .value_kind:     hidden_block_count_y
      - .offset:         184
        .size:           4
        .value_kind:     hidden_block_count_z
      - .offset:         188
        .size:           2
        .value_kind:     hidden_group_size_x
      - .offset:         190
        .size:           2
        .value_kind:     hidden_group_size_y
      - .offset:         192
        .size:           2
        .value_kind:     hidden_group_size_z
      - .offset:         194
        .size:           2
        .value_kind:     hidden_remainder_x
      - .offset:         196
        .size:           2
        .value_kind:     hidden_remainder_y
      - .offset:         198
        .size:           2
        .value_kind:     hidden_remainder_z
      - .offset:         216
        .size:           8
        .value_kind:     hidden_global_offset_x
      - .offset:         224
        .size:           8
        .value_kind:     hidden_global_offset_y
      - .offset:         232
        .size:           8
        .value_kind:     hidden_global_offset_z
      - .offset:         240
        .size:           2
        .value_kind:     hidden_grid_dims
      - .offset:         296
        .size:           4
        .value_kind:     hidden_dynamic_lds_size
    .group_segment_fixed_size: 0
    .kernarg_segment_align: 8
    .kernarg_segment_size: 432
    .language:       OpenCL C
    .language_version:
      - 2
      - 0
    .max_flat_workgroup_size: 512
    .name:           _Z10fwd_kernel4Args
    .private_segment_fixed_size: 0
    .sgpr_count:     108
    .sgpr_spill_count: 55
    .symbol:         _Z10fwd_kernel4Args.kd
    .uniform_work_group_size: 1
    .uses_dynamic_stack: false
    .vgpr_count:     256
    .vgpr_spill_count: 0
    .wavefront_size: 64
